# GEMM tile decode: the rcp-based division by the panel-group size (always 4 for these shapes) replaced by a shift and a mask at 7 sites
# speedup vs baseline: 1.0037x; 1.0037x over previous
.LBB0_165:
	s_or_b64 exec, exec, s[0:1]
	v_readlane_b32 s0, v254, 33
	s_and_b32 s49, s0, 1
	s_add_i32 s7, s49, 5
	s_mul_i32 s68, s7, 0x90
	v_readlane_b32 s2, v253, 38
	v_mov_b32_e32 v0, v209
	s_cmp_lt_i32 s2, s68
	s_waitcnt lgkmcnt(0)
	s_barrier
	s_cselect_b64 s[0:1], -1, 0
	v_readfirstlane_b32 s4, v0
	s_cmp_ge_i32 s2, s68
	s_mul_i32 s18, s7, 18
	s_cbranch_scc1 .LBB0_167
	s_lshl_b32 s2, s7, 2
	s_abs_i32 s3, s2
	v_cvt_f32_u32_e32 v2, s3
	v_readlane_b32 s5, v254, 30
	s_or_b32 s5, s18, s5
	v_readlane_b32 s6, v254, 29
	v_rcp_iflag_f32_e32 v2, v2
	s_mul_i32 s5, s5, s6
	v_readlane_b32 s6, v254, 16
	s_add_i32 s5, s5, s6
	v_mul_f32_e32 v2, 0x4f7ffffe, v2
	v_cvt_u32_f32_e32 v2, v2
	s_sub_i32 s6, 0, s3
	s_abs_i32 s9, s5
	s_xor_b32 s8, s5, s2
	v_readfirstlane_b32 s10, v2
	s_mul_i32 s6, s6, s10
	s_mul_hi_u32 s6, s10, s6
	s_add_i32 s10, s10, s6
	s_mul_hi_u32 s6, s9, s10
	s_mul_i32 s10, s6, s3
	s_sub_i32 s9, s9, s10
	s_ashr_i32 s8, s8, 31
	s_add_i32 s11, s6, 1
	s_sub_i32 s10, s9, s3
	s_cmp_ge_u32 s9, s3
	s_cselect_b32 s6, s11, s6
	s_cselect_b32 s9, s10, s9
	s_add_i32 s10, s6, 1
	s_cmp_ge_u32 s9, s3
	s_cselect_b32 s3, s10, s6
	s_xor_b32 s3, s3, s8
	s_sub_i32 s3, s3, s8
	s_lshl_b32 s6, s3, 2
	s_sub_i32 s8, 0x90, s6
	s_min_i32 s8, s8, 4
	s_mul_i32 s3, s3, s2
	s_sub_i32 s2, s5, s3
	s_lshr_b32 s10, s2, 2
	s_and_b32 s2, s2, 3
	v_readlane_b32 s3, v254, 19
	s_add_i32 s3, s6, s3
	s_add_i32 s12, s3, s2

.LBB0_173:
	s_add_i32 s92, s92, 1
	s_mul_i32 s7, s92, s55
	s_mul_hi_u32 s8, s92, s51
	s_add_i32 s8, s8, s7
	s_mul_i32 s7, s92, s51
	v_readlane_b32 s9, v253, 38
	s_add_u32 s24, s7, s9
	s_addc_u32 s25, s8, s72
	s_waitcnt lgkmcnt(0)
	v_mov_b64_e32 v[2:3], s[68:69]
	v_cmp_ge_i64_e32 vcc, s[24:25], v[2:3]
	v_cmp_lt_i64_e64 s[8:9], s[24:25], v[2:3]
	s_cbranch_vccnz .LBB0_175
	s_ashr_i32 s7, s24, 31
	s_lshr_b32 s7, s7, 29
	s_add_i32 s7, s24, s7
	s_ashr_i32 s11, s7, 3
	s_and_b32 s7, s7, -8
	s_sub_i32 s7, s24, s7
	s_lshr_b32 s13, s7, 31
	s_or_b32 s13, s18, s13
	s_mul_i32 s7, s13, s7
	s_add_i32 s7, s7, s11
	s_abs_i32 s13, s7
	s_mul_hi_u32 s24, s13, s41
	s_mul_i32 s25, s24, s50
	s_ashr_i32 s11, s7, 31
	s_sub_i32 s13, s13, s25
	s_xor_b32 s11, s11, s19
	s_add_i32 s25, s24, 1
	s_sub_i32 s28, s13, s50
	s_cmp_ge_u32 s13, s50
	s_cselect_b32 s24, s25, s24
	s_cselect_b32 s13, s28, s13
	s_add_i32 s25, s24, 1
	s_cmp_ge_u32 s13, s50
	s_cselect_b32 s13, s25, s24
	s_xor_b32 s13, s13, s11
	s_sub_i32 s11, s13, s11
	s_lshl_b32 s13, s11, 2
	s_sub_i32 s24, 0x90, s13
	s_min_i32 s24, s24, 4
	s_mul_i32 s11, s11, s48
	s_sub_i32 s7, s7, s11
	s_lshr_b32 s28, s7, 2
	s_and_b32 s7, s7, 3
	v_readlane_b32 s11, v254, 19
	s_add_i32 s11, s13, s11
	s_add_i32 s30, s11, s7

.LBB0_639:
	s_or_b64 exec, exec, s[36:37]
	s_lshr_b32 s59, s70, 8
	s_lshr_b32 s78, s70, 6
	v_readlane_b32 s2, v253, 38
	v_mov_b32_e32 v0, v209
	s_cmp_lt_i32 s2, s78
	s_waitcnt lgkmcnt(0)
	s_barrier
	s_cselect_b64 s[0:1], -1, 0
	s_cmp_ge_i32 s2, s78
	v_readfirstlane_b32 s8, v0
	s_cbranch_scc1 .LBB0_641
	s_lshr_b32 s2, s70, 9
	v_readlane_b32 s3, v254, 30
	s_or_b32 s2, s2, s3
	v_readlane_b32 s3, v254, 29
	s_mul_i32 s2, s2, s3
	v_readlane_b32 s3, v254, 16
	s_add_i32 s2, s2, s3
	s_ashr_i32 s3, s2, 31
	s_lshr_b32 s3, s3, 28
	s_add_i32 s3, s2, s3
	s_ashr_i32 s4, s3, 4
	s_lshl_b32 s4, s4, 2
	s_sub_i32 s5, s59, s4
	s_min_i32 s5, s5, 4
	s_and_b32 s3, s3, -16
	s_sub_i32 s2, s2, s3
	s_lshr_b32 s22, s2, 2
	s_and_b32 s2, s2, 3
	v_readlane_b32 s3, v254, 19
	s_add_i32 s2, s2, s3
	s_add_i32 s24, s2, s4

.LBB0_647:
	s_add_i32 s39, s39, 1
	s_mul_i32 s8, s39, s55
	s_mul_hi_u32 s9, s39, s51
	s_add_i32 s9, s9, s8
	s_mul_i32 s8, s39, s51
	v_readlane_b32 s15, v253, 38
	s_add_u32 s18, s8, s15
	s_addc_u32 s19, s9, s72
	v_mov_b64_e32 v[2:3], s[78:79]
	v_cmp_ge_i64_e32 vcc, s[18:19], v[2:3]
	v_cmp_lt_i64_e64 s[8:9], s[18:19], v[2:3]
	s_cbranch_vccnz .LBB0_649
	s_ashr_i32 s14, s18, 31
	s_lshr_b32 s14, s14, 29
	s_add_i32 s14, s18, s14
	s_ashr_i32 s15, s14, 3
	s_and_b32 s14, s14, -8
	s_sub_i32 s14, s18, s14
	s_lshr_b32 s16, s14, 31
	s_or_b32 s16, s41, s16
	s_mul_i32 s14, s16, s14
	s_add_i32 s14, s14, s15
	s_ashr_i32 s15, s14, 31
	s_lshr_b32 s15, s15, 28
	s_add_i32 s15, s14, s15
	s_ashr_i32 s16, s15, 4
	s_lshl_b32 s16, s16, 2
	s_sub_i32 s17, s59, s16
	s_min_i32 s17, s17, 4
	s_and_b32 s15, s15, -16
	s_sub_i32 s15, s14, s15
	s_lshr_b32 s14, s15, 2
	s_and_b32 s15, s15, 3
	v_readlane_b32 s17, v254, 19
	s_add_i32 s16, s16, s17
	s_add_i32 s16, s16, s15

.LBB0_780:
	s_add_i32 s37, s37, 1
	s_mul_i32 s0, s37, s55
	s_mul_hi_u32 s1, s37, s51
	s_add_i32 s1, s1, s0
	s_mul_i32 s0, s37, s51
	v_readlane_b32 s15, v253, 38
	s_add_u32 s18, s0, s15
	s_addc_u32 s19, s1, s72
	v_mov_b64_e32 v[2:3], s[8:9]
	v_cmp_ge_i64_e32 vcc, s[18:19], v[2:3]
	v_cmp_lt_i64_e64 s[0:1], s[18:19], v[2:3]
	s_cbranch_vccnz .LBB0_782
	s_ashr_i32 s14, s18, 31
	s_lshr_b32 s14, s14, 29
	s_add_i32 s14, s18, s14
	s_ashr_i32 s15, s14, 3
	s_and_b32 s14, s14, -8
	s_sub_i32 s14, s18, s14
	s_cmp_lt_i32 s14, 0
	s_cselect_b32 s16, s30, s29
	s_mul_i32 s14, s16, s14
	s_add_i32 s14, s14, s15
	s_mul_hi_i32 s15, s14, 0x2e8ba2e9
	s_lshr_b32 s16, s15, 31
	s_ashr_i32 s15, s15, 4
	s_add_i32 s15, s15, s16
	s_lshl_b32 s16, s15, 2
	s_sub_i32 s17, s59, s16
	s_min_i32 s17, s17, 4
	s_mulk_i32 s15, 0x58
	s_sub_i32 s15, s14, s15
	s_lshr_b32 s14, s15, 2
	s_and_b32 s15, s15, 3
	v_readlane_b32 s17, v254, 19
	s_add_i32 s16, s16, s17
	s_add_i32 s16, s16, s15

.LBB0_834:
	s_or_b64 exec, exec, s[46:47]
	v_mov_b32_e32 v0, v209
	s_waitcnt lgkmcnt(0)
	s_barrier
	s_and_b64 vcc, exec, s[52:53]
	v_readfirstlane_b32 s0, v0
	s_cbranch_vccnz .LBB0_836
	s_lshr_b32 s1, s70, 9
	v_readlane_b32 s2, v254, 30
	s_or_b32 s1, s1, s2
	v_readlane_b32 s2, v254, 29
	s_mul_i32 s1, s1, s2
	v_readlane_b32 s2, v254, 16
	s_add_i32 s1, s1, s2
	s_ashr_i32 s2, s1, 31
	s_lshr_b32 s2, s2, 28
	s_add_i32 s2, s1, s2
	s_ashr_i32 s3, s2, 4
	s_lshl_b32 s3, s3, 2
	s_sub_i32 s4, s59, s3
	s_min_i32 s4, s4, 4
	s_and_b32 s2, s2, -16
	s_sub_i32 s1, s1, s2
	s_lshr_b32 s41, s1, 2
	s_and_b32 s1, s1, 3
	v_readlane_b32 s2, v254, 19
	s_add_i32 s1, s1, s2
	s_add_i32 s16, s1, s3

.LBB0_842:
	s_add_i32 s34, s34, 1
	s_mul_i32 s4, s34, s55
	s_mul_hi_u32 s5, s34, s51
	s_add_i32 s5, s5, s4
	s_mul_i32 s4, s34, s51
	v_readlane_b32 s8, v253, 38
	s_add_u32 s4, s4, s8
	s_addc_u32 s5, s5, s72
	v_mov_b64_e32 v[2:3], s[78:79]
	v_cmp_ge_i64_e32 vcc, s[4:5], v[2:3]
	v_cmp_lt_i64_e64 s[8:9], s[4:5], v[2:3]
	s_cbranch_vccnz .LBB0_844
	s_ashr_i32 s5, s4, 31
	s_lshr_b32 s5, s5, 29
	s_add_i32 s5, s4, s5
	s_ashr_i32 s14, s5, 3
	s_and_b32 s5, s5, -8
	s_sub_i32 s4, s4, s5
	s_lshr_b32 s5, s4, 31
	s_or_b32 s5, s35, s5
	s_mul_i32 s4, s5, s4
	s_add_i32 s4, s4, s14
	s_ashr_i32 s5, s4, 31
	s_lshr_b32 s5, s5, 28
	s_add_i32 s5, s4, s5
	s_ashr_i32 s14, s5, 4
	s_lshl_b32 s14, s14, 2
	s_sub_i32 s15, s59, s14
	s_min_i32 s15, s15, 4
	s_and_b32 s5, s5, -16
	s_sub_i32 s4, s4, s5
	s_lshr_b32 s36, s4, 2
	s_and_b32 s4, s4, 3
	v_readlane_b32 s5, v254, 19
	s_add_i32 s5, s14, s5
	s_add_i32 s37, s5, s4
